# scan phase: chunk section after the staging barrier de-serialised (LDS reads for the scale/convert step and the first MFMA operand sets issued together, counted lgkmcnt waits, operands read one MFMA a
# speedup vs baseline: 1.0117x; 1.0068x over previous
; #define LAS __attribute__((address_space(3)))
; DI unsigned pk2(float lo, float hi) { unsigned r; asm("v_cvt_pk_bf16_f32 %0, %1, %2" : "=v"(r) : "v"(lo), "v"(hi)); return r; }
; DI void phase_scan(int l, int wv, bool fill, bool last) {
;     ...
;             {   const int kb = w >> 1, vb = w & 1;
;                 const LAS float* er = (const LAS float*)(L + O_EV) + kb * 32 + 4 * hh; const LAS float* ebr = er + 128; const LAS float* eb = er + 256;
; #pragma unroll
;                 for (int g = 0; g < 4; ++g) { const f32x4 e4 = *(const LAS f32x4*)(er + 8 * g);
;                     u32x2 pk; pk.x = pk2(S[4 * g] * e4.x, S[4 * g + 1] * e4.y); pk.y = pk2(S[4 * g + 2] * e4.z, S[4 * g + 3] * e4.w);
;                     *(LAS u32x2*)(L + O_ST + (vb * 32 + r32) * RS + (kb * 32 + 8 * g + 4 * hh) * 2) = pk; }
;                 f32x16 U;
; #pragma unroll
;                 for (int i = 0; i < 16; ++i) U[i] = 0.f;
; #pragma unroll
;                 for (int ks = 0; ks < 4; ++ks) { const bf16x8v a = tr_frag(L + O_KT, RS, ks * 16 + 8 * hh, kb * 32, lane), bv = tr_frag(L + O_V, RS64, ks * 16 + 8 * hh, vb * 32, lane);
;                     U = __builtin_amdgcn_mfma_f32_32x32x16_bf16(a, bv, U, 0, 0, 0); }
; #pragma unroll
;                 for (int g = 0; g < 4; ++g) { const f32x4 b4 = *(const LAS f32x4*)(eb + 8 * g), c4 = *(const LAS f32x4*)(ebr + 8 * g);
;                     S[4 * g] = b4.x * S[4 * g] + c4.x * U[4 * g]; S[4 * g + 1] = b4.y * S[4 * g + 1] + c4.y * U[4 * g + 1]; S[4 * g + 2] = b4.z * S[4 * g + 2] + c4.z * U[4 * g + 2]; S[4 * g + 3] = b4.w * S[4 * g + 3] + c4.w * U[4 * g + 3]; }
.LBB0_494:
	s_waitcnt lgkmcnt(0)
	s_barrier
	ds_read_b128 v[88:91], v189
	ds_read_b128 v[92:95], v189 offset:32
	ds_read_b128 v[96:99], v189 offset:64
	ds_read_b128 v[100:103], v189 offset:96
	ds_read_b64_tr_b16 v[16:17], v201 offset:17408
	ds_read_b64_tr_b16 v[18:19], v201 offset:18496
	ds_read_b64_tr_b16 v[20:21], v231 offset:52224
	ds_read_b64_tr_b16 v[22:23], v231 offset:52800
	ds_read_b64_tr_b16 v[24:25], v201 offset:21760
	ds_read_b64_tr_b16 v[26:27], v201 offset:22848
	ds_read_b64_tr_b16 v[28:29], v231 offset:54528
	ds_read_b64_tr_b16 v[30:31], v231 offset:55104
	s_cmp_gt_u32 s78, 3
	v_readlane_b32 s62, v254, 33
	s_cselect_b64 s[60:61], -1, 0
	v_readlane_b32 s63, v254, 34
	s_waitcnt lgkmcnt(11)
	v_mul_f32_e32 v8, v168, v88
	v_mul_f32_e32 v9, v169, v89
	v_mul_f32_e32 v10, v170, v90
	v_mul_f32_e32 v11, v171, v91
	v_cvt_pk_bf16_f32 v104, v8, v9
	v_cvt_pk_bf16_f32 v105, v10, v11
	ds_write_b64 v200, v[104:105] offset:34816
	s_or_b64 s[60:61], s[62:63], s[60:61]
	s_and_b64 s[62:63], s[54:55], s[60:61]
	s_andn2_b64 vcc, exec, s[62:63]
	s_waitcnt lgkmcnt(11)
	v_mul_f32_e32 v8, v172, v92
	v_mul_f32_e32 v9, v173, v93
	v_mul_f32_e32 v10, v174, v94
	v_mul_f32_e32 v11, v175, v95
	v_cvt_pk_bf16_f32 v106, v8, v9
	v_cvt_pk_bf16_f32 v107, v10, v11
	ds_write_b64 v200, v[106:107] offset:34832
	s_waitcnt lgkmcnt(11)
	v_mul_f32_e32 v8, v176, v96
	v_mul_f32_e32 v9, v177, v97
	v_mul_f32_e32 v10, v178, v98
	v_mul_f32_e32 v11, v179, v99
	v_cvt_pk_bf16_f32 v108, v8, v9
	v_cvt_pk_bf16_f32 v109, v10, v11
	ds_write_b64 v200, v[108:109] offset:34848
	s_waitcnt lgkmcnt(11)
	v_mul_f32_e32 v8, v180, v100
	v_mul_f32_e32 v9, v181, v101
	v_mul_f32_e32 v10, v182, v102
	v_mul_f32_e32 v11, v183, v103
	v_cvt_pk_bf16_f32 v110, v8, v9
	v_cvt_pk_bf16_f32 v111, v10, v11
	ds_write_b64 v200, v[110:111] offset:34864
	s_waitcnt lgkmcnt(8)
	v_mfma_f32_32x32x16_bf16 v[0:15], v[16:19], v[20:23], 0
	ds_read_b64_tr_b16 v[16:17], v201 offset:26112
	ds_read_b64_tr_b16 v[18:19], v201 offset:27200
	ds_read_b64_tr_b16 v[20:21], v231 offset:56832
	ds_read_b64_tr_b16 v[22:23], v231 offset:57408
	s_waitcnt lgkmcnt(8)
	v_mfma_f32_32x32x16_bf16 v[0:15], v[24:27], v[28:31], v[0:15]
	ds_read_b64_tr_b16 v[24:25], v201 offset:30464
	ds_read_b64_tr_b16 v[26:27], v201 offset:31552
	ds_read_b64_tr_b16 v[28:29], v231 offset:59136
	ds_read_b64_tr_b16 v[30:31], v231 offset:59712
	s_waitcnt lgkmcnt(4)
	v_mfma_f32_32x32x16_bf16 v[0:15], v[16:19], v[20:23], v[0:15]
	ds_read_b128 v[88:91], v189 offset:1024
	ds_read_b128 v[108:111], v189 offset:512
	ds_read_b128 v[100:103], v189 offset:544
	ds_read_b128 v[92:95], v189 offset:1056
	ds_read_b128 v[96:99], v189 offset:1088
	ds_read_b128 v[112:115], v189 offset:576
	ds_read_b128 v[104:107], v189 offset:1120
	ds_read_b128 v[116:119], v189 offset:608
	s_waitcnt lgkmcnt(8)
	v_mfma_f32_32x32x16_bf16 v[0:15], v[24:27], v[28:31], v[0:15]
	s_cbranch_vccnz .LBB0_498
	v_mov_b32_e32 v16, 0
	s_mov_b32 s62, 0
	v_mov_b32_e32 v17, v16
	v_mov_b32_e32 v18, v16
	v_mov_b32_e32 v19, v16
	v_mov_b32_e32 v20, v16
	v_mov_b32_e32 v21, v16
	v_mov_b32_e32 v22, v16
	v_mov_b32_e32 v23, v16
	v_mov_b32_e32 v24, v16
	v_mov_b32_e32 v25, v16
	v_mov_b32_e32 v26, v16
	v_mov_b32_e32 v27, v16
	v_mov_b32_e32 v28, v16
	v_mov_b32_e32 v29, v16
	v_mov_b32_e32 v30, v16
	v_mov_b32_e32 v31, v16
